# FFN-up conv epilogue: paired LDS reads (ds_read2), two rows per bf16 convert with d16_hi stores, unmasked store path when all 8 rows are valid
# speedup vs baseline: 1.0132x; 1.0045x over previous
.Lcv5_loop:
	v_add_u32_e32 v36, 1032, v17
	v_add_u32_e32 v37, 2064, v17
	v_add_u32_e32 v38, 3096, v17
	ds_read2_b32 v[188:189], v17 offset0:0 offset1:64
	ds_read2_b32 v[190:191], v17 offset0:129 offset1:193
	ds_read2_b32 v[192:193], v36 offset0:0 offset1:64
	ds_read2_b32 v[194:195], v36 offset0:129 offset1:193
	ds_read2_b32 v[196:197], v37 offset0:0 offset1:64
	ds_read2_b32 v[198:199], v37 offset0:129 offset1:193
	ds_read2_b32 v[200:201], v38 offset0:0 offset1:64
	ds_read2_b32 v[202:203], v38 offset0:129 offset1:193
	v_add_u32_e32 v32, s63, v18
	v_ashrrev_i32_e32 v220, 7, v32
	v_and_b32_e32 v24, 0x7f, v32
	v_mad_u32_u24 v220, v220, 44, s14
	v_subrev_u32_e32 v33, 64, v24
	v_lshlrev_b32_e32 v24, 7, v24
	v_sub_u32_e32 v34, v40, v32
	v_lshl_or_b32 v24, v220, 14, v24
	v_add_u32_e32 v24, v24, v41
	v_add_u32_e32 v35, 0xac000, v24
	v_cmp_le_i32_e64 s[6:7], 63, v33
	v_cmp_le_i32_e64 s[8:9], 62, v33
	v_cmp_le_i32_e64 vcc, 61, v33
	v_cndmask_b32_e64 v25, v24, v35, s[6:7]
	v_cmp_le_i32_e64 s[6:7], 60, v33
	v_cndmask_b32_e64 v26, v24, v35, s[8:9]
	v_cmp_le_i32_e64 s[8:9], 59, v33
	v_cndmask_b32_e64 v27, v24, v35, vcc
	v_cmp_le_i32_e64 vcc, 58, v33
	v_cndmask_b32_e64 v28, v24, v35, s[6:7]
	v_cmp_le_i32_e64 s[6:7], 57, v33
	v_cndmask_b32_e64 v29, v24, v35, s[8:9]
	v_cndmask_b32_e64 v30, v24, v35, vcc
	s_nop 0
	v_cndmask_b32_e64 v31, v24, v35, s[6:7]
	s_waitcnt lgkmcnt(0)
	v_fma_f32 v204, v3, v15, v9
	v_fma_f32 v212, v2, v14, v8
	v_fma_f32 v205, v3, v10, v9
	v_fma_f32 v213, v2, v11, v8
	v_fma_f32 v206, v3, v188, v9
	v_fma_f32 v214, v2, v189, v8
	v_fma_f32 v207, v3, v190, v9
	v_fma_f32 v215, v2, v191, v8
	v_fma_f32 v208, v3, v192, v9
	v_fma_f32 v216, v2, v193, v8
	v_fma_f32 v209, v3, v194, v9
	v_fma_f32 v217, v2, v195, v8
	v_fma_f32 v210, v3, v196, v9
	v_fma_f32 v218, v2, v197, v8
	v_fma_f32 v211, v3, v198, v9
	v_fma_f32 v219, v2, v199, v8
	v_fma_f32 v204, v5, v10, v204
	v_fma_f32 v212, v4, v11, v212
	v_fma_f32 v205, v5, v188, v205
	v_fma_f32 v213, v4, v189, v213
	v_fma_f32 v206, v5, v190, v206
	v_fma_f32 v214, v4, v191, v214
	v_fma_f32 v207, v5, v192, v207
	v_fma_f32 v215, v4, v193, v215
	v_fma_f32 v208, v5, v194, v208
	v_fma_f32 v216, v4, v195, v216
	v_fma_f32 v209, v5, v196, v209
	v_fma_f32 v217, v4, v197, v217
	v_fma_f32 v210, v5, v198, v210
	v_fma_f32 v218, v4, v199, v218
	v_fma_f32 v211, v5, v200, v211
	v_fma_f32 v219, v4, v201, v219
	v_fma_f32 v204, v7, v188, v204
	v_fma_f32 v212, v6, v189, v212
	v_fma_f32 v205, v7, v190, v205
	v_fma_f32 v213, v6, v191, v213
	v_fma_f32 v206, v7, v192, v206
	v_fma_f32 v214, v6, v193, v214
	v_fma_f32 v207, v7, v194, v207
	v_fma_f32 v215, v6, v195, v215
	v_fma_f32 v208, v7, v196, v208
	v_fma_f32 v216, v6, v197, v216
	v_fma_f32 v209, v7, v198, v209
	v_fma_f32 v217, v6, v199, v217
	v_fma_f32 v210, v7, v200, v210
	v_fma_f32 v218, v6, v201, v218
	v_fma_f32 v211, v7, v202, v211
	v_fma_f32 v219, v6, v203, v219
	v_mul_f32_e32 v220, 0xbfb8aa3b, v204
	v_mul_f32_e32 v221, 0xbfb8aa3b, v205
	v_mul_f32_e32 v222, 0xbfb8aa3b, v206
	v_mul_f32_e32 v223, 0xbfb8aa3b, v207
	v_mul_f32_e32 v224, 0xbfb8aa3b, v208
	v_mul_f32_e32 v225, 0xbfb8aa3b, v209
	v_mul_f32_e32 v226, 0xbfb8aa3b, v210
	v_mul_f32_e32 v227, 0xbfb8aa3b, v211
	v_exp_f32_e32 v220, v220
	v_exp_f32_e32 v221, v221
	v_exp_f32_e32 v222, v222
	v_exp_f32_e32 v223, v223
	v_exp_f32_e32 v224, v224
	v_exp_f32_e32 v225, v225
	v_exp_f32_e32 v226, v226
	v_exp_f32_e32 v227, v227
	v_add_f32_e32 v220, 1.0, v220
	v_add_f32_e32 v221, 1.0, v221
	v_add_f32_e32 v222, 1.0, v222
	v_add_f32_e32 v223, 1.0, v223
	v_add_f32_e32 v224, 1.0, v224
	v_add_f32_e32 v225, 1.0, v225
	v_add_f32_e32 v226, 1.0, v226
	v_add_f32_e32 v227, 1.0, v227
	v_rcp_f32_e32 v220, v220
	v_rcp_f32_e32 v221, v221
	v_rcp_f32_e32 v222, v222
	v_rcp_f32_e32 v223, v223
	v_rcp_f32_e32 v224, v224
	v_rcp_f32_e32 v225, v225
	v_rcp_f32_e32 v226, v226
	v_rcp_f32_e32 v227, v227
	v_mov_b32_e32 v15, v200
	v_mov_b32_e32 v10, v202
	v_mov_b32_e32 v14, v201
	v_mov_b32_e32 v11, v203
	v_mul_f32_e32 v204, v204, v220
	v_mul_f32_e32 v205, v205, v221
	v_mul_f32_e32 v206, v206, v222
	v_mul_f32_e32 v207, v207, v223
	v_mul_f32_e32 v208, v208, v224
	v_mul_f32_e32 v209, v209, v225
	v_mul_f32_e32 v210, v210, v226
	v_mul_f32_e32 v211, v211, v227
	v_mul_f32_e32 v212, v212, v204
	v_mul_f32_e32 v213, v213, v205
	v_mul_f32_e32 v214, v214, v206
	v_mul_f32_e32 v215, v215, v207
	v_mul_f32_e32 v216, v216, v208
	v_mul_f32_e32 v217, v217, v209
	v_mul_f32_e32 v218, v218, v210
	v_mul_f32_e32 v219, v219, v211
	v_cvt_pk_bf16_f32 v212, v212, v213
	v_cvt_pk_bf16_f32 v214, v214, v215
	v_cvt_pk_bf16_f32 v216, v216, v217
	v_cvt_pk_bf16_f32 v218, v218, v219
	v_cmp_gt_i32_e32 vcc, 8, v34
	s_cmp_lg_u64 vcc, 0
	s_cbranch_scc1 .Lcv5_slow
	global_store_short v24, v212, s[42:43]
	global_store_short_d16_hi v25, v212, s[42:43] offset:128
	global_store_short v26, v214, s[42:43] offset:256
	global_store_short_d16_hi v27, v214, s[42:43] offset:384
	global_store_short v28, v216, s[42:43] offset:512
	global_store_short_d16_hi v29, v216, s[42:43] offset:640
	global_store_short v30, v218, s[42:43] offset:768
	global_store_short_d16_hi v31, v218, s[42:43] offset:896
	s_branch .Lcv5_next
.Lcv5_slow:
	v_cmp_lt_i32_e32 vcc, 0, v34
	s_and_b64 exec, exec, vcc
	global_store_short v24, v212, s[42:43]
	v_cmp_lt_i32_e32 vcc, 1, v34
	s_and_b64 exec, exec, vcc
	global_store_short_d16_hi v25, v212, s[42:43] offset:128
	v_cmp_lt_i32_e32 vcc, 2, v34
	s_and_b64 exec, exec, vcc
	global_store_short v26, v214, s[42:43] offset:256
	v_cmp_lt_i32_e32 vcc, 3, v34
	s_and_b64 exec, exec, vcc
	global_store_short_d16_hi v27, v214, s[42:43] offset:384
	v_cmp_lt_i32_e32 vcc, 4, v34
	s_and_b64 exec, exec, vcc
	global_store_short v28, v216, s[42:43] offset:512
	v_cmp_lt_i32_e32 vcc, 5, v34
	s_and_b64 exec, exec, vcc
	global_store_short_d16_hi v29, v216, s[42:43] offset:640
	v_cmp_lt_i32_e32 vcc, 6, v34
	s_and_b64 exec, exec, vcc
	global_store_short v30, v218, s[42:43] offset:768
	v_cmp_lt_i32_e32 vcc, 7, v34
	s_and_b64 exec, exec, vcc
	global_store_short_d16_hi v31, v218, s[42:43] offset:896
	s_mov_b64 exec, -1
.Lcv5_next:
	v_add_u32_e32 v17, 0x1020, v17
	v_add_u32_e32 v18, 8, v18
	s_sub_u32 s62, s62, 1
	s_cmp_lg_u32 s62, 0
	s_cbranch_scc1 .Lcv5_loop
	s_branch .LBB0_646

.Lcv12_loop:
	v_add_u32_e32 v36, 1032, v17
	v_add_u32_e32 v37, 2064, v17
	v_add_u32_e32 v38, 3096, v17
	ds_read2_b32 v[188:189], v17 offset0:0 offset1:64
	ds_read2_b32 v[190:191], v17 offset0:129 offset1:193
	ds_read2_b32 v[192:193], v36 offset0:0 offset1:64
	ds_read2_b32 v[194:195], v36 offset0:129 offset1:193
	ds_read2_b32 v[196:197], v37 offset0:0 offset1:64
	ds_read2_b32 v[198:199], v37 offset0:129 offset1:193
	ds_read2_b32 v[200:201], v38 offset0:0 offset1:64
	ds_read2_b32 v[202:203], v38 offset0:129 offset1:193
	v_add_u32_e32 v32, s63, v18
	v_ashrrev_i32_e32 v220, 7, v32
	v_and_b32_e32 v24, 0x7f, v32
	v_mad_u32_u24 v220, v220, 44, s18
	v_subrev_u32_e32 v33, 64, v24
	v_lshlrev_b32_e32 v24, 7, v24
	v_sub_u32_e32 v34, v40, v32
	v_lshl_or_b32 v24, v220, 14, v24
	v_add_u32_e32 v24, v24, v41
	v_add_u32_e32 v35, 0xac000, v24
	v_cmp_le_i32_e64 s[6:7], 63, v33
	v_cmp_le_i32_e64 s[8:9], 62, v33
	v_cmp_le_i32_e64 vcc, 61, v33
	v_cndmask_b32_e64 v25, v24, v35, s[6:7]
	v_cmp_le_i32_e64 s[6:7], 60, v33
	v_cndmask_b32_e64 v26, v24, v35, s[8:9]
	v_cmp_le_i32_e64 s[8:9], 59, v33
	v_cndmask_b32_e64 v27, v24, v35, vcc
	v_cmp_le_i32_e64 vcc, 58, v33
	v_cndmask_b32_e64 v28, v24, v35, s[6:7]
	v_cmp_le_i32_e64 s[6:7], 57, v33
	v_cndmask_b32_e64 v29, v24, v35, s[8:9]
	v_cndmask_b32_e64 v30, v24, v35, vcc
	s_nop 0
	v_cndmask_b32_e64 v31, v24, v35, s[6:7]
	s_waitcnt lgkmcnt(0)
	v_fma_f32 v204, v3, v15, v9
	v_fma_f32 v212, v2, v14, v8
	v_fma_f32 v205, v3, v10, v9
	v_fma_f32 v213, v2, v11, v8
	v_fma_f32 v206, v3, v188, v9
	v_fma_f32 v214, v2, v189, v8
	v_fma_f32 v207, v3, v190, v9
	v_fma_f32 v215, v2, v191, v8
	v_fma_f32 v208, v3, v192, v9
	v_fma_f32 v216, v2, v193, v8
	v_fma_f32 v209, v3, v194, v9
	v_fma_f32 v217, v2, v195, v8
	v_fma_f32 v210, v3, v196, v9
	v_fma_f32 v218, v2, v197, v8
	v_fma_f32 v211, v3, v198, v9
	v_fma_f32 v219, v2, v199, v8
	v_fma_f32 v204, v5, v10, v204
	v_fma_f32 v212, v4, v11, v212
	v_fma_f32 v205, v5, v188, v205
	v_fma_f32 v213, v4, v189, v213
	v_fma_f32 v206, v5, v190, v206
	v_fma_f32 v214, v4, v191, v214
	v_fma_f32 v207, v5, v192, v207
	v_fma_f32 v215, v4, v193, v215
	v_fma_f32 v208, v5, v194, v208
	v_fma_f32 v216, v4, v195, v216
	v_fma_f32 v209, v5, v196, v209
	v_fma_f32 v217, v4, v197, v217
	v_fma_f32 v210, v5, v198, v210
	v_fma_f32 v218, v4, v199, v218
	v_fma_f32 v211, v5, v200, v211
	v_fma_f32 v219, v4, v201, v219
	v_fma_f32 v204, v7, v188, v204
	v_fma_f32 v212, v6, v189, v212
	v_fma_f32 v205, v7, v190, v205
	v_fma_f32 v213, v6, v191, v213
	v_fma_f32 v206, v7, v192, v206
	v_fma_f32 v214, v6, v193, v214
	v_fma_f32 v207, v7, v194, v207
	v_fma_f32 v215, v6, v195, v215
	v_fma_f32 v208, v7, v196, v208
	v_fma_f32 v216, v6, v197, v216
	v_fma_f32 v209, v7, v198, v209
	v_fma_f32 v217, v6, v199, v217
	v_fma_f32 v210, v7, v200, v210
	v_fma_f32 v218, v6, v201, v218
	v_fma_f32 v211, v7, v202, v211
	v_fma_f32 v219, v6, v203, v219
	v_mul_f32_e32 v220, 0xbfb8aa3b, v204
	v_mul_f32_e32 v221, 0xbfb8aa3b, v205
	v_mul_f32_e32 v222, 0xbfb8aa3b, v206
	v_mul_f32_e32 v223, 0xbfb8aa3b, v207
	v_mul_f32_e32 v224, 0xbfb8aa3b, v208
	v_mul_f32_e32 v225, 0xbfb8aa3b, v209
	v_mul_f32_e32 v226, 0xbfb8aa3b, v210
	v_mul_f32_e32 v227, 0xbfb8aa3b, v211
	v_exp_f32_e32 v220, v220
	v_exp_f32_e32 v221, v221
	v_exp_f32_e32 v222, v222
	v_exp_f32_e32 v223, v223
	v_exp_f32_e32 v224, v224
	v_exp_f32_e32 v225, v225
	v_exp_f32_e32 v226, v226
	v_exp_f32_e32 v227, v227
	v_add_f32_e32 v220, 1.0, v220
	v_add_f32_e32 v221, 1.0, v221
	v_add_f32_e32 v222, 1.0, v222
	v_add_f32_e32 v223, 1.0, v223
	v_add_f32_e32 v224, 1.0, v224
	v_add_f32_e32 v225, 1.0, v225
	v_add_f32_e32 v226, 1.0, v226
	v_add_f32_e32 v227, 1.0, v227
	v_rcp_f32_e32 v220, v220
	v_rcp_f32_e32 v221, v221
	v_rcp_f32_e32 v222, v222
	v_rcp_f32_e32 v223, v223
	v_rcp_f32_e32 v224, v224
	v_rcp_f32_e32 v225, v225
	v_rcp_f32_e32 v226, v226
	v_rcp_f32_e32 v227, v227
	v_mov_b32_e32 v15, v200
	v_mov_b32_e32 v10, v202
	v_mov_b32_e32 v14, v201
	v_mov_b32_e32 v11, v203
	v_mul_f32_e32 v204, v204, v220
	v_mul_f32_e32 v205, v205, v221
	v_mul_f32_e32 v206, v206, v222
	v_mul_f32_e32 v207, v207, v223
	v_mul_f32_e32 v208, v208, v224
	v_mul_f32_e32 v209, v209, v225
	v_mul_f32_e32 v210, v210, v226
	v_mul_f32_e32 v211, v211, v227
	v_mul_f32_e32 v212, v212, v204
	v_mul_f32_e32 v213, v213, v205
	v_mul_f32_e32 v214, v214, v206
	v_mul_f32_e32 v215, v215, v207
	v_mul_f32_e32 v216, v216, v208
	v_mul_f32_e32 v217, v217, v209
	v_mul_f32_e32 v218, v218, v210
	v_mul_f32_e32 v219, v219, v211
	v_cvt_pk_bf16_f32 v212, v212, v213
	v_cvt_pk_bf16_f32 v214, v214, v215
	v_cvt_pk_bf16_f32 v216, v216, v217
	v_cvt_pk_bf16_f32 v218, v218, v219
	v_cmp_gt_i32_e32 vcc, 8, v34
	s_cmp_lg_u64 vcc, 0
	s_cbranch_scc1 .Lcv12_slow
	global_store_short v24, v212, s[42:43]
	global_store_short_d16_hi v25, v212, s[42:43] offset:128
	global_store_short v26, v214, s[42:43] offset:256
	global_store_short_d16_hi v27, v214, s[42:43] offset:384
	global_store_short v28, v216, s[42:43] offset:512
	global_store_short_d16_hi v29, v216, s[42:43] offset:640
	global_store_short v30, v218, s[42:43] offset:768
	global_store_short_d16_hi v31, v218, s[42:43] offset:896
	s_branch .Lcv12_next
